# v22 + out-proj epilogue: residual tile cache lines touched up front so the serialized residual loads hit L2
# baseline (speedup 1.0000x reference)
.LBB0_601:
	s_or_b64 exec, exec, s[22:23]
	s_lshl_b32 s4, s42, 5
	v_readlane_b32 s36, v254, 10
	s_lshl_b32 s5, s12, 8
	s_lshl_b32 s64, s93, 11
	v_readlane_b32 s40, v254, 14
	v_readlane_b32 s41, v254, 15
	v_readlane_b32 s44, v254, 18
	v_readlane_b32 s45, v254, 19
	v_readlane_b32 s46, v254, 20
	v_readlane_b32 s47, v254, 21
	v_readlane_b32 s48, v254, 22
	v_readlane_b32 s49, v254, 23
	v_lshrrev_b32_e32 v128, 1, v142
	s_or_b32 s4, s5, s4
	s_lshl_b64 s[56:57], s[64:65], 2
	v_readlane_b32 s37, v254, 11
	v_readlane_b32 s38, v254, 12
	v_readlane_b32 s39, v254, 13
	s_mov_b64 s[48:49], s[40:41]
	v_and_or_b32 v174, v128, 24, s4
	s_add_u32 s4, s48, s56
	s_addc_u32 s5, s49, s57
	v_ashrrev_i32_e32 v175, 31, v174
	s_waitcnt lgkmcnt(0)
	s_barrier
	v_lshl_add_u64 v[132:133], v[174:175], 2, s[4:5]
	global_load_dwordx4 v[136:139], v[132:133], off offset:16
	global_load_dwordx4 v[140:143], v[132:133], off
	global_load_dwordx4 v[128:131], v[132:133], off offset:528
	s_nop 0
	global_load_dwordx4 v[132:135], v[132:133], off offset:512
	v_lshl_add_u32 v237, v188, 2, 0
	ds_read_b32 v160, v237 offset:4096
	v_add_u32_e32 v220, s26, v188
	v_ashrrev_i32_e32 v221, 31, v220
	v_lshlrev_b64 v[144:145], 11, v[220:221]
	v_readlane_b32 s4, v255, 14
	s_cmp_lg_u32 s93, 0
	v_lshl_add_u64 v[164:165], v[144:145], 0, v[174:175]
	v_readlane_b32 s5, v255, 15
	s_cselect_b64 s[24:25], -1, 0
	s_cmp_eq_u32 s93, 0
	v_lshl_add_u64 v[168:169], v[164:165], 1, s[4:5]
	v_readlane_b32 s42, v254, 16
	v_readlane_b32 s43, v254, 17
	v_readlane_b32 s50, v254, 24
	v_readlane_b32 s51, v254, 25
	s_mov_b64 s[46:47], s[38:39]
	s_mov_b64 s[44:45], s[36:37]
	s_cbranch_scc1 .LBB0_680
	global_load_dword v229, v[168:169], off offset:256
	s_mov_b64 s[100:101], 0x10000
	v_lshl_add_u64 v[226:227], v[168:169], 0, s[100:101]
	global_load_dword v229, v[226:227], off
	global_load_dword v229, v[226:227], off offset:256
	s_mov_b64 s[100:101], 0x20000
	v_lshl_add_u64 v[226:227], v[168:169], 0, s[100:101]
	global_load_dword v229, v[226:227], off
	global_load_dword v229, v[226:227], off offset:256
	s_mov_b64 s[100:101], 0x30000
	v_lshl_add_u64 v[226:227], v[168:169], 0, s[100:101]
	global_load_dword v229, v[226:227], off
	global_load_dword v229, v[226:227], off offset:256
	s_mov_b64 s[100:101], 0x80000
	v_lshl_add_u64 v[226:227], v[168:169], 0, s[100:101]
	global_load_dword v229, v[226:227], off
	global_load_dword v229, v[226:227], off offset:256
	s_mov_b64 s[100:101], 0x90000
	v_lshl_add_u64 v[226:227], v[168:169], 0, s[100:101]
	global_load_dword v229, v[226:227], off
	global_load_dword v229, v[226:227], off offset:256
	s_mov_b64 s[100:101], 0xa0000
	v_lshl_add_u64 v[226:227], v[168:169], 0, s[100:101]
	global_load_dword v229, v[226:227], off
	global_load_dword v229, v[226:227], off offset:256
	s_mov_b64 s[100:101], 0xb0000
	v_lshl_add_u64 v[226:227], v[168:169], 0, s[100:101]
	global_load_dword v229, v[226:227], off
	global_load_dword v229, v[226:227], off offset:256
	global_load_dwordx4 v[144:147], v[168:169], off
	s_waitcnt vmcnt(0)
	v_lshlrev_b32_e32 v148, 16, v144
	v_and_b32_e32 v149, 0xffff0000, v144
	v_lshlrev_b32_e32 v150, 16, v145
	v_and_b32_e32 v151, 0xffff0000, v145
	v_lshlrev_b32_e32 v144, 16, v146
	v_and_b32_e32 v145, 0xffff0000, v146
	v_lshlrev_b32_e32 v146, 16, v147
	v_and_b32_e32 v147, 0xffff0000, v147
	s_cbranch_execnz .LBB0_604
.LBB0_603:
	v_readlane_b32 s36, v254, 10
	v_readlane_b32 s37, v254, 11
	v_readlane_b32 s38, v254, 12
	v_readlane_b32 s39, v254, 13
	v_lshl_add_u64 v[226:227], v[164:165], 2, s[36:37]
	global_load_dword v229, v[226:227], off offset:512
	v_lshl_add_u64 v[148:149], v[164:165], 2, s[36:37]
	global_load_dwordx4 v[144:147], v[148:149], off offset:16
	s_mov_b64 s[100:101], 0x20000
	v_lshl_add_u64 v[226:227], v[148:149], 0, s[100:101]
	global_load_dword v229, v[226:227], off
	global_load_dword v229, v[226:227], off offset:512
	s_mov_b64 s[100:101], 0x40000
	v_lshl_add_u64 v[226:227], v[148:149], 0, s[100:101]
	global_load_dword v229, v[226:227], off
	global_load_dword v229, v[226:227], off offset:512
	s_mov_b64 s[100:101], 0x60000
	v_lshl_add_u64 v[226:227], v[148:149], 0, s[100:101]
	global_load_dword v229, v[226:227], off
	global_load_dword v229, v[226:227], off offset:512
	s_mov_b64 s[100:101], 0x100000
	v_lshl_add_u64 v[226:227], v[148:149], 0, s[100:101]
	global_load_dword v229, v[226:227], off
	global_load_dword v229, v[226:227], off offset:512
	s_mov_b64 s[100:101], 0x120000
	v_lshl_add_u64 v[226:227], v[148:149], 0, s[100:101]
	global_load_dword v229, v[226:227], off
	global_load_dword v229, v[226:227], off offset:512
	s_mov_b64 s[100:101], 0x140000
	v_lshl_add_u64 v[226:227], v[148:149], 0, s[100:101]
	global_load_dword v229, v[226:227], off
	global_load_dword v229, v[226:227], off offset:512
	s_mov_b64 s[100:101], 0x160000
	v_lshl_add_u64 v[226:227], v[148:149], 0, s[100:101]
	global_load_dword v229, v[226:227], off
	global_load_dword v229, v[226:227], off offset:512
	s_nop 0
	global_load_dwordx4 v[148:151], v[148:149], off
	v_readlane_b32 s40, v254, 14
	v_readlane_b32 s41, v254, 15
	v_readlane_b32 s42, v254, 16
	v_readlane_b32 s43, v254, 17
	v_readlane_b32 s44, v254, 18
	v_readlane_b32 s45, v254, 19
	v_readlane_b32 s46, v254, 20
	v_readlane_b32 s47, v254, 21
	v_readlane_b32 s48, v254, 22
	v_readlane_b32 s49, v254, 23
	v_readlane_b32 s50, v254, 24
	v_readlane_b32 s51, v254, 25

	.amdhsa_kernel _Z14fwd_megakernel6Params
		.amdhsa_group_segment_fixed_size 0
		.amdhsa_private_segment_fixed_size 0
		.amdhsa_kernarg_size 368
		.amdhsa_user_sgpr_count 2
		.amdhsa_user_sgpr_dispatch_ptr 0
		.amdhsa_user_sgpr_queue_ptr 0
		.amdhsa_user_sgpr_kernarg_segment_ptr 1
		.amdhsa_user_sgpr_dispatch_id 0
		.amdhsa_user_sgpr_kernarg_preload_length 0
		.amdhsa_user_sgpr_kernarg_preload_offset 0
		.amdhsa_user_sgpr_private_segment_size 0
		.amdhsa_uses_dynamic_stack 0
		.amdhsa_enable_private_segment 0
		.amdhsa_system_sgpr_workgroup_id_x 1
		.amdhsa_system_sgpr_workgroup_id_y 0
		.amdhsa_system_sgpr_workgroup_id_z 0
		.amdhsa_system_sgpr_workgroup_info 0
		.amdhsa_system_vgpr_workitem_id 2
		.amdhsa_next_free_vgpr 256
		.amdhsa_next_free_sgpr 102
		.amdhsa_accum_offset 256
		.amdhsa_reserve_vcc 1
		.amdhsa_float_round_mode_32 0
		.amdhsa_float_round_mode_16_64 0
		.amdhsa_float_denorm_mode_32 3
		.amdhsa_float_denorm_mode_16_64 3
		.amdhsa_dx10_clamp 1
		.amdhsa_ieee_mode 1
		.amdhsa_fp16_overflow 0
		.amdhsa_tg_split 0
		.amdhsa_exception_fp_ieee_invalid_op 0
		.amdhsa_exception_fp_denorm_src 0
		.amdhsa_exception_fp_ieee_div_zero 0
		.amdhsa_exception_fp_ieee_overflow 0
		.amdhsa_exception_fp_ieee_underflow 0
		.amdhsa_exception_fp_ieee_inexact 0
		.amdhsa_exception_int_div_zero 0
	.end_amdhsa_kernel

amdhsa.kernels:
  - .agpr_count:     0
    .args:
      - .offset:         0
        .size:           112
        .value_kind:     by_value
      - .offset:         112
        .size:           4
        .value_kind:     hidden_block_count_x
      - .offset:         116
        .size:           4
        .value_kind:     hidden_block_count_y
      - .offset:         120
        .size:           4
        .value_kind:     hidden_block_count_z
      - .offset:         124
        .size:           2
        .value_kind:     hidden_group_size_x
      - .offset:         126
        .size:           2
        .value_kind:     hidden_group_size_y
      - .offset:         128
        .size:           2
        .value_kind:     hidden_group_size_z
      - .offset:         130
        .size:           2
        .value_kind:     hidden_remainder_x
      - .offset:         132
        .size:           2
        .value_kind:     hidden_remainder_y
      - .offset:         134
        .size:           2
        .value_kind:     hidden_remainder_z
      - .offset:         152
        .size:           8
        .value_kind:     hidden_global_offset_x
      - .offset:         160
        .size:           8
        .value_kind:     hidden_global_offset_y
      - .offset:         168
        .size:           8
        .value_kind:     hidden_global_offset_z
      - .offset:         176
        .size:           2
        .value_kind:     hidden_grid_dims
      - .offset:         200
        .size:           8
        .value_kind:     hidden_multigrid_sync_arg
      - .offset:         232
        .size:           4
        .value_kind:     hidden_dynamic_lds_size
    .group_segment_fixed_size: 0
    .kernarg_segment_align: 8
    .kernarg_segment_size: 368
    .language:       OpenCL C
    .language_version:
      - 2
      - 0
    .max_flat_workgroup_size: 512
    .name:           _Z14fwd_megakernel6Params
    .private_segment_fixed_size: 0
    .sgpr_count:     108
    .sgpr_spill_count: 115
    .symbol:         _Z14fwd_megakernel6Params.kd
    .uniform_work_group_size: 1
    .uses_dynamic_stack: false
    .vgpr_count:     256
    .vgpr_spill_count: 0
    .wavefront_size: 64
